# EpiF: only the permlane-swap row sums (scale loads and their wait kept); same layout as previous
# speedup vs baseline: 1.0068x; 1.0068x over previous
.LBB0_191:
	v_mov_b32_e32 v158, v160
	s_mov_b32 s40, s16
	v_mov_b32_e32 v159, v161
	s_mov_b32 s92, s23
	s_lshl_b32 s41, s48, 8
	s_lshl_b32 s48, s99, 8
	s_lshl_b32 s68, s92, 5
	s_add_i32 s68, s68, s48
	v_lshl_add_u32 v156, v159, 3, s68
	v_ashrrev_i32_e32 v157, 31, v156
	v_lshl_add_u64 v[110:111], v[156:157], 2, s[44:45]
	global_load_dwordx4 v[122:125], v[110:111], off offset:16
	global_load_dwordx4 v[126:129], v[110:111], off
	global_load_dwordx4 v[106:109], v[110:111], off offset:528
	s_nop 0
	global_load_dwordx4 v[110:113], v[110:111], off offset:512
	s_lshl_b32 s40, s40, 6
	s_add_i32 s40, s40, s41
	v_add_u32_e32 v158, s40, v158
	v_cmp_eq_u32_e32 vcc, 0, v159
	v_ashrrev_i32_e32 v159, 31, v158
	v_lshlrev_b64 v[164:165], 11, v[158:159]
	s_lshl_b32 s94, s99, 2
	s_ashr_i32 s95, s94, 31
	s_ashr_i32 s93, s92, 31
	s_waitcnt vmcnt(0)
	v_pk_mul_f32 v[166:167], v[140:141], v[124:125]
	v_pk_mul_f32 v[144:145], v[144:145], v[128:129]
	v_pk_mul_f32 v[142:143], v[142:143], v[126:127]
	v_pk_mul_f32 v[140:141], v[138:139], v[122:123]
	v_mul_f32_e32 v138, v143, v143
	v_mul_f32_e32 v139, v145, v145
	v_fmac_f32_e32 v138, v142, v142
	v_fmac_f32_e32 v139, v144, v144
	v_add_f32_e32 v138, v138, v139
	v_mul_f32_e32 v139, v141, v141
	v_fmac_f32_e32 v139, v140, v140
	v_add_f32_e32 v138, v138, v139
	v_mul_f32_e32 v139, v167, v167
	v_fmac_f32_e32 v139, v166, v166
	v_add_f32_e32 v168, v139, v138
	v_cvt_pk_bf16_f32 v138, v142, v143
	v_lshl_add_u64 v[142:143], s[62:63], 0, v[164:165]
	v_cvt_pk_bf16_f32 v139, v144, v145
	v_lshl_add_u64 v[142:143], v[156:157], 1, v[142:143]
	v_pk_mul_f32 v[136:137], v[136:137], v[112:113]
	v_pk_mul_f32 v[134:135], v[134:135], v[110:111]
	v_cvt_pk_bf16_f32 v140, v140, v141
	v_cvt_pk_bf16_f32 v141, v166, v167
	global_store_dwordx4 v[142:143], v[138:141], off
	s_nop 1
	v_pk_mul_f32 v[138:139], v[132:133], v[108:109]
	v_pk_mul_f32 v[132:133], v[130:131], v[106:107]
	v_mul_f32_e32 v130, v135, v135
	v_mul_f32_e32 v131, v137, v137
	v_fmac_f32_e32 v130, v134, v134
	v_fmac_f32_e32 v131, v136, v136
	v_add_f32_e32 v130, v130, v131
	v_mul_f32_e32 v131, v133, v133
	v_fmac_f32_e32 v131, v132, v132
	v_add_f32_e32 v130, v130, v131
	v_mul_f32_e32 v131, v139, v139
	v_fmac_f32_e32 v131, v138, v138
	v_add_f32_e32 v130, v131, v130
	v_cvt_pk_bf16_f32 v131, v136, v137
	v_add_f32_e32 v140, v168, v130
	v_cvt_pk_bf16_f32 v130, v134, v135
	v_cvt_pk_bf16_f32 v132, v132, v133
	v_cvt_pk_bf16_f32 v133, v138, v139
	global_store_dwordx4 v[142:143], v[130:133], off offset:256
	s_nop 1
	v_and_b32_e32 v131, 64, v231
	v_xor_b32_e32 v130, 16, v231
	v_add_u32_e32 v131, 64, v131
	v_cmp_lt_i32_e64 s[40:41], v130, v131
	v_xor_b32_e32 v133, 32, v231
	s_nop 0
	v_cndmask_b32_e64 v130, v231, v130, s[40:41]
	v_lshlrev_b32_e32 v132, 2, v130
	v_mov_b32_e32 v132, v140
	v_mov_b32_e32 v130, v140
	s_nop 1
	v_permlane16_swap_b32_e32 v132, v130
	v_cmp_lt_i32_e64 s[40:41], v133, v131
	s_waitcnt lgkmcnt(0)
	v_add_f32_e32 v130, v132, v130
	v_cndmask_b32_e64 v131, v231, v133, s[40:41]
	v_lshlrev_b32_e32 v133, 2, v131
	v_mov_b32_e32 v131, v130
	s_nop 1
	v_permlane32_swap_b32_e32 v130, v131
	s_and_saveexec_b64 s[40:41], vcc
	s_cbranch_execz .LBB0_193
	v_lshlrev_b64 v[134:135], 6, v[158:159]
	v_lshl_add_u64 v[134:135], s[76:77], 0, v[134:135]
	v_lshl_add_u64 v[134:135], s[94:95], 2, v[134:135]
	v_lshl_add_u64 v[134:135], s[92:93], 2, v[134:135]
	s_waitcnt lgkmcnt(0)
	v_add_f32_e32 v130, v130, v131
	global_store_dword v[134:135], v130, off

.LBB0_228:
	s_nop 0
	s_nop 0
	s_nop 0
	s_nop 0
	s_nop 0
	s_nop 0
	s_nop 0
	s_nop 0
	s_mov_b64 s[26:27], 0
